# v26 + phase-6 tail de-stacking: GLU tile index uses bid^0x80 so the layer-0 extra GLU tiles land on workgroups without context attention units
# baseline (speedup 1.0000x reference)
; #define LAS __attribute__((address_space(3)))
; #define PG8_STAGE(bufoff, gbase, voff) do { _Pragma("unroll") for (int _i = 0; _i < 2; ++_i) \
;         __builtin_amdgcn_global_load_lds((const unsigned*)((const char*)(gbase) + (voff)[_i]), (LAS unsigned*)(lds + (bufoff) + ldsw + _i * 8192), 16, 0, 0); } while (0)
; #define PG8_WAIT_V(n) asm volatile("s_waitcnt vmcnt(" #n ")" ::: "memory")
; #define PG8_BAR __builtin_amdgcn_s_barrier()
; __device__ __forceinline__ bool tile_of(int L, int nM, int nN, int& pm, int& pn) {
;     const int nwg = nM * nN; if (L >= nwg) return false;
;     int wgid = (int)L; { const int q = nwg / 8, r = nwg % 8, xcd = wgid % 8, off = wgid / 8; wgid = (xcd < r ? xcd * (q + 1) : r * (q + 1) + (xcd - r) * q) + off; }
;     const int nig = WGM * nN, gid = wgid / nig, fm = gid * WGM, gsz = (nM - fm) < WGM ? (nM - fm) : WGM;
;     pm = fm + ((wgid % nig) % gsz); pn = (wgid % nig) / gsz; return true;
; }
; template <class Epi, class Sched, bool ALIGN_EPI, bool SP2, bool PERMA = false>
; __device__ __forceinline__ void gemm_phase(LAS unsigned char* lds, const int tid, const int lda, const int ldb, const Sched& S, const Epi& E) {
;     const int wid = __builtin_amdgcn_readfirstlane(tid >> 6), lane = tid & 63, wr = wid >> 2, wc = wid & 3, fr = lane & 15, fq = lane >> 4;
;     unsigned voffA[2], voffB[2];
; #pragma unroll
;     for (int i = 0; i < 2; ++i) { int R, C; stage_rc(tid * 16 + i * 8192, R, C);
;         const int Ra = PERMA ? (128 * (R >> 6) + 8 * (R & 15) + ((R >> 4) & 3)) : R;
;         voffA[i] = (unsigned)(Ra * lda + C) * 2u; voffB[i] = (unsigned)(R * ldb + C) * 2u; }
;     ...
;     if constexpr (SP2) {
;         PG8_STAGE(PG8_SB(0, 0), cB, voffB); PG8_STAGE(PG8_SB(0, 1), cB + hsB, voffB); PG8_STAGE(PG8_SA(0, 0), cA, voffA); PG8_STAGE(PG8_SA(0, 1), cA + hsA, voffA);
;         if (wr == 1) PG8_BAR;
;         PG8_WAIT_V(2); PG8_BAR;
;         PG8_STAGE(PG8_SB(1, 0), cB + kstep, voffB); PG8_STAGE(PG8_SA(1, 0), cA + kstep, voffA); PG8_STAGE(PG8_SB(1, 1), cB + hsB + kstep, voffB);
.LBB0_371:
	s_andn2_b64 vcc, exec, s[0:1]
	s_cbranch_vccnz .LBB0_694
	v_readlane_b32 s0, v253, 31
	s_cmp_lt_i32 s0, 3
	s_mov_b64 s[0:1], -1
	s_cbranch_scc1 .LBB0_479
	v_readlane_b32 s0, v253, 31
	s_cmp_lt_i32 s0, 4
	s_mov_b64 s[0:1], -1
	s_cbranch_scc1 .LBB0_465
	v_readlane_b32 s0, v253, 31
	s_cmp_gt_i32 s0, 5
	s_mov_b64 s[0:1], -1
	s_cbranch_scc0 .LBB0_428
	v_readlane_b32 s0, v254, 4
	v_readlane_b32 s8, v254, 34
	s_xor_b32 s8, s8, 0x80
	s_cmp_ge_i32 s8, s0
	v_readfirstlane_b32 s2, v196
	v_readlane_b32 s9, v254, 35
	s_cbranch_scc1 .LBB0_391
	v_lshlrev_b32_e32 v0, 4, v196
	v_add_u32_e32 v1, 0x2000, v0
	v_ashrrev_i32_e32 v2, 31, v1
	v_lshrrev_b32_e32 v2, 22, v2
	v_add_u32_e32 v2, v1, v2
	v_ashrrev_i32_e32 v8, 10, v2
	v_mul_i32_i24_e32 v3, 0x400, v8
	v_sub_u32_e32 v1, v1, v3
	v_lshrrev_b32_e32 v3, 4, v1
	v_bitop3_b32 v1, v3, v1, 32 bitop3:0x6c
	v_ashrrev_i32_e32 v3, 31, v1
	v_lshrrev_b32_e32 v3, 26, v3
	v_add_u32_e32 v3, v1, v3
	v_ashrrev_i32_e32 v9, 6, v3
	v_and_b32_e32 v3, 0xc0, v3
	v_sub_u32_e32 v1, v1, v3
	v_lshlrev_b32_e32 v2, 5, v8
	v_ashrrev_i16_sdwa v1, v244, sext(v1) dst_sel:DWORD dst_unused:UNUSED_PAD src0_sel:DWORD src1_sel:BYTE_0
	v_and_b32_e32 v2, 32, v2
	v_bfe_i32 v10, v1, 0, 16
	v_readlane_b32 s6, v254, 42
	v_add_u32_e32 v1, v2, v10
	v_lshlrev_b32_e32 v2, 3, v8
	v_readlane_b32 s7, v254, 43
	s_add_u32 s0, s6, 0xcb00400
	v_and_b32_e32 v2, 0x3ffff0, v2
	s_addc_u32 s1, s7, 0
	v_add_lshl_u32 v2, v9, v2, 10
	s_add_u32 s50, s6, 0xf80000
	s_waitcnt vmcnt(0)
	v_lshl_add_u32 v156, v1, 1, v2
	s_addc_u32 s13, s7, 0
	v_add_u32_e32 v158, v156, v2
	v_bfe_i32 v2, v196, 27, 1
	s_ashr_i32 s6, s8, 31
	v_lshrrev_b32_e32 v2, 22, v2
	s_lshr_b32 s6, s6, 29
	v_add_u32_e32 v2, v0, v2
	s_add_i32 s6, s8, s6
	s_ashr_i32 s3, s2, 6
	v_and_b32_e32 v2, 0xfffffc00, v2
	s_ashr_i32 s7, s6, 3
	s_and_b32 s6, s6, -8
	s_ashr_i32 s10, s2, 8
	s_lshl_b32 s94, s3, 10
	v_sub_u32_e32 v0, v0, v2
	s_sub_i32 s6, s8, s6
	v_lshrrev_b32_e32 v2, 4, v0
	s_cmp_lt_i32 s6, 0
	v_readlane_b32 s8, v254, 6
	v_readlane_b32 s9, v254, 7
	v_bitop3_b32 v0, v2, v0, 32 bitop3:0x6c
	s_cselect_b32 s8, s9, s8
	v_ashrrev_i32_e32 v2, 31, v0
	s_mul_i32 s6, s6, s8
	v_ashrrev_i32_e32 v1, 31, v196
	v_lshrrev_b32_e32 v2, 26, v2
	s_add_i32 s6, s6, s7
	v_lshrrev_b32_e32 v1, 26, v1
	v_add_u32_e32 v2, v0, v2
	s_ashr_i32 s7, s6, 31
	v_add_u32_e32 v1, v196, v1
	v_ashrrev_i32_e32 v12, 6, v2
	v_and_b32_e32 v2, 0xc0, v2
	s_lshr_b32 s7, s7, 29
	v_ashrrev_i32_e32 v11, 6, v1
	v_sub_u32_e32 v0, v0, v2
	s_add_i32 s7, s6, s7
	v_lshlrev_b32_e32 v1, 5, v11
	v_ashrrev_i16_sdwa v0, v244, sext(v0) dst_sel:DWORD dst_unused:UNUSED_PAD src0_sel:DWORD src1_sel:BYTE_0
	s_ashr_i32 s8, s7, 3
	v_and_b32_e32 v1, 32, v1
	v_bfe_i32 v13, v0, 0, 16
	s_lshl_b32 s9, s8, 2
	v_readlane_b32 s8, v254, 5
	v_add_u32_e32 v0, v1, v13
	v_lshlrev_b32_e32 v1, 3, v11
	s_sub_i32 s8, s8, s9
	v_and_b32_e32 v1, 0x3ffff0, v1
	s_min_i32 s11, s8, 4
	v_add_lshl_u32 v1, v12, v1, 10
	s_sext_i32_i8 s8, s11
	v_lshl_add_u32 v192, v0, 1, v1
	v_cvt_f32_i32_e32 v0, s8
	s_and_b32 s7, s7, -8
	s_sub_i32 s12, s6, s7
	v_add_u32_e32 v160, v192, v1
	v_cvt_f32_i32_e32 v1, s12
	v_rcp_iflag_f32_e32 v2, v0
	s_xor_b32 s6, s12, s8
	s_ashr_i32 s6, s6, 30
	s_or_b32 s8, s6, 1
	v_mul_f32_e32 v2, v1, v2
	v_trunc_f32_e32 v2, v2
	v_fma_f32 v1, -v2, v0, v1
	v_cvt_i32_f32_e32 v2, v2
	v_cmp_ge_f32_e64 s[6:7], |v1|, |v0|
	s_and_b64 s[6:7], s[6:7], exec
	s_cselect_b32 s6, s8, 0
	v_readfirstlane_b32 s7, v2
	s_add_i32 s8, s7, s6
	s_mul_i32 s6, s8, s11
	s_sub_i32 s6, s12, s6
	s_sext_i32_i8 s6, s6
	s_add_i32 s16, s9, s6
	s_ashr_i32 s17, s16, 31
	s_lshl_b64 s[6:7], s[16:17], 19
	s_add_u32 s28, s0, s6
	s_addc_u32 s29, s1, s7
	s_bfe_i64 s[6:7], s[8:9], 0x80000
	s_lshl_b64 s[6:7], s[6:7], 18
	s_add_u32 s30, s50, s6
	s_addc_u32 s31, s13, s7
	s_add_i32 s95, s94, 0
	s_add_i32 m0, s95, 0x10000
	v_writelane_b32 v254, s13, 46
	global_load_lds_dwordx4 v192, s[30:31]
	s_add_i32 m0, s95, 0x12000
	s_add_u32 s6, s30, 0x20000
	global_load_lds_dwordx4 v156, s[30:31]
	s_addc_u32 s7, s31, 0
	s_add_i32 m0, s95, 0x14000
	s_add_i32 s96, s95, 0x2000
	global_load_lds_dwordx4 v192, s[6:7]
	s_add_i32 m0, s95, 0x16000
	s_add_u32 s12, s28, 0x40000
	global_load_lds_dwordx4 v156, s[6:7]
	s_mov_b32 m0, s95
	s_addc_u32 s13, s29, 0
	global_load_lds_dwordx4 v160, s[28:29]
	s_mov_b32 m0, s96
	s_add_i32 s97, s95, 0x4000
	global_load_lds_dwordx4 v158, s[28:29]
	s_mov_b32 m0, s97
	s_add_i32 s6, s95, 0x6000
	global_load_lds_dwordx4 v160, s[12:13]
	s_mov_b32 m0, s6
	s_cmp_eq_u32 s10, 1
	global_load_lds_dwordx4 v158, s[12:13]
	s_cselect_b64 s[12:13], -1, 0
	v_mov_b32_e32 v157, v193
	v_mov_b32_e32 v161, v193
	v_mov_b32_e32 v159, v193
	v_writelane_b32 v254, s12, 47
	v_lshl_add_u64 v[4:5], s[30:31], 0, v[192:193]
	v_lshl_add_u64 v[2:3], s[30:31], 0, v[156:157]
	v_lshl_add_u64 v[0:1], s[28:29], 0, v[160:161]
	v_writelane_b32 v254, s13, 48
	s_cmp_lg_u32 s10, 1
	v_lshl_add_u64 v[6:7], s[28:29], 0, v[158:159]
	s_cbranch_scc1 .LBB0_378
	s_barrier

; __device__ __forceinline__ bool tile_of(int L, int nM, int nN, int& pm, int& pn) {
;     const int nwg = nM * nN; if (L >= nwg) return false;
;     int wgid = (int)L; { const int q = nwg / 8, r = nwg % 8, xcd = wgid % 8, off = wgid / 8; wgid = (xcd < r ? xcd * (q + 1) : r * (q + 1) + (xcd - r) * q) + off; }
;     const int nig = WGM * nN, gid = wgid / nig, fm = gid * WGM, gsz = (nM - fm) < WGM ? (nM - fm) : WGM;
;     pm = fm + ((wgid % nig) % gsz); pn = (wgid % nig) / gsz; return true;
; }
; template <class Epi, class Sched, bool ALIGN_EPI, bool SP2, bool PERMA = false>
; __device__ __forceinline__ void gemm_phase(LAS unsigned char* lds, const int tid, const int lda, const int ldb, const Sched& S, const Epi& E) {
;     ...
;         const bool has_next = S.next(ui + 1, nxt);
;     __device__ __forceinline__ bool next(int i, Unit& u) const {
;         int pm, pn; if (!pg8::tile_of(i * G + c, nM, nN, pm, pn)) return false;
;         u.A = A + (size_t)pm * 256 * lda; u.B = B + (size_t)pn * 256 * ldb; u.nt = nt; u.pm = pm0 + pm; u.pn = pn; u.mode = 0; return true;
.LBB0_381:
	s_add_i32 s22, s22, 1
	v_readlane_b32 s2, v254, 36
	s_mul_i32 s2, s22, s2
	v_readlane_b32 s14, v254, 34
	s_xor_b32 s14, s14, 0x80
	s_add_i32 s2, s2, s14
	v_readlane_b32 s3, v254, 4
	v_readlane_b32 s15, v254, 35
	s_cmp_lt_i32 s2, s3
	s_cselect_b64 s[14:15], -1, 0
	s_cmp_ge_i32 s2, s3
	s_cbranch_scc1 .LBB0_383
	s_ashr_i32 s3, s2, 31
	s_lshr_b32 s3, s3, 29
	s_add_i32 s3, s2, s3
	s_ashr_i32 s12, s3, 3
	s_and_b32 s3, s3, -8
	s_sub_i32 s2, s2, s3
	s_cmp_lt_i32 s2, 0
	v_readlane_b32 s3, v254, 6
	v_readlane_b32 s13, v254, 7
	s_cselect_b32 s3, s13, s3
	s_mul_i32 s2, s2, s3
	s_add_i32 s2, s2, s12
	s_ashr_i32 s3, s2, 31
	s_lshr_b32 s3, s3, 29
	s_add_i32 s3, s2, s3
	s_ashr_i32 s12, s3, 3
	s_lshl_b32 s13, s12, 2
	v_readlane_b32 s12, v254, 5
	s_sub_i32 s12, s12, s13
	s_min_i32 s17, s12, 4
	s_abs_i32 s12, s17
	v_cvt_f32_u32_e32 v0, s12
	s_sub_i32 s20, 0, s12
	s_and_b32 s3, s3, -8
	s_sub_i32 s2, s2, s3
	v_rcp_iflag_f32_e32 v0, v0
	s_abs_i32 s3, s2
	s_xor_b32 s19, s2, s17
	s_ashr_i32 s19, s19, 31
	v_mul_f32_e32 v0, 0x4f7ffffe, v0
	v_cvt_u32_f32_e32 v0, v0
	s_mov_b32 s24, s23
	v_readfirstlane_b32 s21, v0
	s_mul_i32 s20, s20, s21
	s_mul_hi_u32 s20, s21, s20
	s_add_i32 s21, s21, s20
	s_mul_hi_u32 s20, s3, s21
	s_mul_i32 s21, s20, s12
	s_sub_i32 s3, s3, s21
	s_add_i32 s23, s20, 1
	s_sub_i32 s21, s3, s12
	s_cmp_ge_u32 s3, s12
	s_cselect_b32 s20, s23, s20
	s_cselect_b32 s3, s21, s3
	s_add_i32 s21, s20, 1
	s_cmp_ge_u32 s3, s12
	s_cselect_b32 s3, s21, s20
	s_xor_b32 s3, s3, s19
	s_sub_i32 s12, s3, s19
	s_mul_i32 s3, s12, s17
	s_sub_i32 s2, s2, s3
	s_add_i32 s20, s13, s2
	s_ashr_i32 s21, s20, 31
	s_lshl_b64 s[2:3], s[20:21], 19
	s_mov_b32 s23, s24
	s_add_u32 s24, s0, s2
	s_addc_u32 s25, s1, s3
	s_ashr_i32 s13, s12, 31
	s_lshl_b64 s[2:3], s[12:13], 18
	s_add_u32 s26, s50, s2
	v_readlane_b32 s2, v254, 46
	s_addc_u32 s27, s2, s3
